# phase 0 input conversion (f32 -> bf16 + row sum of squares): all 16 row loads issued before the first wait, which becomes vmcnt(12) (was vmcnt(0) after the first 4 loads)
# speedup vs baseline: 1.0029x; 1.0029x over previous
.LBB0_505:
	v_add_co_u32_e32 v0, vcc, 0xffffd000, v70
	s_nop 1
	v_addc_co_u32_e32 v1, vcc, -1, v71, vcc
	global_load_dwordx4 v[60:63], v[0:1], off offset:-3072
	global_load_dwordx4 v[56:59], v[0:1], off offset:-2048
	global_load_dwordx4 v[52:55], v[0:1], off offset:-1024
	global_load_dwordx4 v[48:51], v[0:1], off
	v_add_co_u32_e32 v0, vcc, 0xffffe000, v70
	s_nop 1
	v_addc_co_u32_e32 v1, vcc, -1, v71, vcc
	global_load_dwordx4 v[44:47], v[0:1], off offset:-3072
	global_load_dwordx4 v[40:43], v[0:1], off offset:-2048
	global_load_dwordx4 v[36:39], v[0:1], off offset:-1024
	global_load_dwordx4 v[32:35], v[0:1], off
	v_add_co_u32_e32 v0, vcc, 0xfffff000, v70
	s_nop 1
	v_addc_co_u32_e32 v1, vcc, -1, v71, vcc
	global_load_dwordx4 v[28:31], v[0:1], off offset:-3072
	global_load_dwordx4 v[24:27], v[0:1], off offset:-2048
	global_load_dwordx4 v[20:23], v[0:1], off offset:-1024
	s_waitcnt lgkmcnt(0)
	global_load_dwordx4 v[16:19], v[70:71], off offset:-4096
	global_load_dwordx4 v[12:15], v[70:71], off offset:-3072
	global_load_dwordx4 v[8:11], v[70:71], off offset:-2048
	global_load_dwordx4 v[4:7], v[70:71], off offset:-1024
	global_load_dwordx4 v[0:3], v[70:71], off
	s_waitcnt vmcnt(12)
	v_mul_f32_e32 v65, v61, v61
	v_mul_f32_e32 v78, v57, v57
	v_fmac_f32_e32 v65, v60, v60
	v_fmac_f32_e32 v78, v56, v56
	v_fmac_f32_e32 v65, v62, v62
	v_fmac_f32_e32 v78, v58, v58
	v_fmac_f32_e32 v65, v63, v63
	v_fmac_f32_e32 v78, v59, v59
	v_add_f32_e32 v65, v65, v78
	v_mul_f32_e32 v78, v53, v53
	v_fmac_f32_e32 v78, v52, v52
	v_fmac_f32_e32 v78, v54, v54
	v_fmac_f32_e32 v78, v55, v55
	v_add_f32_e32 v65, v65, v78
	v_mul_f32_e32 v78, v49, v49
	v_fmac_f32_e32 v78, v48, v48
	v_fmac_f32_e32 v78, v50, v50
	v_fmac_f32_e32 v78, v51, v51
	v_add_f32_e32 v65, v65, v78
	ds_bpermute_b32 v78, v72, v65
	s_waitcnt lgkmcnt(0)
	v_add_f32_e32 v65, v65, v78
	ds_bpermute_b32 v78, v73, v65
	s_waitcnt lgkmcnt(0)
	v_add_f32_e32 v65, v65, v78
	ds_bpermute_b32 v78, v74, v65
	s_waitcnt lgkmcnt(0)
	v_add_f32_e32 v65, v65, v78
	ds_bpermute_b32 v78, v75, v65
	s_waitcnt lgkmcnt(0)
	v_add_f32_e32 v65, v65, v78
	ds_bpermute_b32 v78, v76, v65
	s_waitcnt lgkmcnt(0)
	v_add_f32_e32 v65, v65, v78
	ds_bpermute_b32 v78, v77, v65
	s_and_saveexec_b64 s[30:31], s[42:43]
	s_cbranch_execz .LBB0_507
	s_waitcnt lgkmcnt(0)
	v_add_f32_e32 v65, v65, v78
	v_cndmask_b32_e64 v65, 0, v65, s[44:45]
	global_store_dword v[66:67], v65, off offset:-192
